# prep items remapped: a block now handles both head-pairs halves of one 64-token tile on the XCD that produced its proj rows
# speedup vs baseline: 1.0415x; 1.0055x over previous
.LBB0_332:
.Lprep2_entry:
	s_lshr_b32 s34, s101, 2
	v_and_b32_e32 v35, 63, v178
	v_lshrrev_b32_e32 v36, 6, v178
	v_and_b32_e32 v37, 15, v35
	v_lshrrev_b32_e32 v38, 4, v35
	s_nop 0
	v_readfirstlane_b32 s0, v36
	s_lshl_b32 s34, s34, 6
	s_lshl_b32 s0, s0, 4
	s_add_u32 s34, s34, s0
	s_and_b32 s1, s101, 3
	s_add_u32 s0, s15, s34
	v_add_u32_e32 v39, s0, v37
	v_and_b32_e32 v39, 0xfff, v39
	v_cmp_ne_u32_e32 vcc, 0, v39
	s_nop 1
	v_cndmask_b32_e64 v5, 0, -1, vcc
	s_movk_i32 s0, 0x1b00
	v_mul_lo_u32 v0, v37, s0
	v_lshlrev_b32_e32 v1, 4, v38
	v_lshlrev_b32_e32 v33, 5, v38
	s_lshl_b32 s0, s1, 8
	v_lshl_add_u32 v2, v38, 3, v0
	v_add_u32_e32 v2, s0, v2
	v_add_u32_e32 v4, v0, v1
	s_lshl_b32 s0, s1, 9
	v_add_u32_e32 v1, s0, v1
	v_lshlrev_b32_e32 v39, 7, v37
	s_lshl_b32 s0, s1, 14
	v_lshl_add_u32 v6, v38, 4, v39
	v_add_u32_e32 v6, s0, v6
	v_lshlrev_b32_e32 v39, 6, v37
	s_lshl_b32 s0, s1, 13
	v_lshl_add_u32 v7, v38, 4, v39
	v_add_u32_e32 v7, s0, v7
	v_lshlrev_b32_e32 v39, 10, v37
	s_lshl_b32 s0, s1, 8
	v_lshl_add_u32 v8, v38, 3, v39
	v_add_u32_e32 v8, s0, v8
	s_add_u32 s0, s15, s34
	s_lshl_b32 s0, s0, 10
	v_add_u32_e32 v8, s0, v8
	s_movk_i32 s0, 0x3e00
	v_mul_lo_u32 v36, v36, s0
	s_movk_i32 s0, 0x90
	v_mul_lo_u32 v39, v37, s0
	v_add_u32_e32 v9, v36, v39
	v_lshl_add_u32 v9, v38, 3, v9
	v_lshrrev_b32_e32 v39, 3, v35
	v_and_b32_e32 v35, 7, v35
	v_mul_lo_u32 v10, v39, s0
	v_add_u32_e32 v10, v36, v10
	v_lshl_add_u32 v10, v35, 4, v10
	v_lshlrev_b32_e32 v11, 10, v39
	v_lshl_add_u32 v11, v35, 4, v11
	s_lshl_b32 s0, s1, 8
	v_add_u32_e32 v11, s0, v11
	s_lshl_b32 s0, s34, 10
	v_add_u32_e32 v11, s0, v11
	v_add_u32_e32 v32, 0x2000, v11
	v_readlane_b32 s0, v233, 62
	v_readlane_b32 s1, v233, 63
	s_nop 4
	s_load_dwordx4 s[60:63], s[0:1], 0x40
	s_load_dwordx2 s[50:51], s[0:1], 0x50
	s_load_dwordx2 s[52:53], s[0:1], 0x60
	s_load_dwordx2 s[54:55], s[0:1], 0x70
	s_load_dwordx4 s[56:59], s[0:1], 0x80
	v_readlane_b32 s32, v234, 33
	s_mul_i32 s0, s34, 0x1b00
	s_add_u32 s40, s24, 0xa247000
	s_addc_u32 s41, s25, 0
	s_add_u32 s40, s40, s0
	s_addc_u32 s41, s41, 0
	s_sub_u32 s42, s40, 0x1b00
	s_subb_u32 s43, s41, 0
	s_sub_u32 s32, s32, 1
	s_waitcnt lgkmcnt(0)
	s_mul_i32 s0, s32, 0x1a00
	s_add_u32 s60, s60, s0
	s_addc_u32 s61, s61, 0
	s_add_u32 s46, s60, 0x800
	s_addc_u32 s47, s61, 0
	s_add_u32 s60, s60, 0x1800
	s_addc_u32 s61, s61, 0
	s_lshl_b32 s0, s32, 11
	s_add_u32 s50, s50, s0
	s_addc_u32 s51, s51, 0
	s_add_u32 s52, s52, s0
	s_addc_u32 s53, s53, 0
	s_add_u32 s56, s56, s0
	s_addc_u32 s57, s57, 0
	s_add_u32 s58, s58, s0
	s_addc_u32 s59, s59, 0
	s_max_i32 s1, s32, 1
	s_sub_u32 s1, s1, 1
	s_lshl_b32 s0, s1, 11
	s_add_u32 s54, s54, s0
	s_addc_u32 s55, s55, 0
	s_lshl_b32 s0, s1, 7
	s_add_u32 s62, s62, s0
	s_addc_u32 s63, s63, 0
	global_load_dwordx4 v[40:43], v4, s[40:41] offset:3072
	global_load_dwordx4 v[56:59], v4, s[40:41] offset:3136
	global_load_dwordx4 v[72:75], v4, s[40:41] offset:3200
	global_load_dwordx4 v[88:91], v4, s[40:41] offset:3264
	s_mov_b32 exec_lo, 0x10001
	s_mov_b32 exec_hi, 0x10001
	global_load_dwordx4 v[44:47], v4, s[42:43] offset:3072
	global_load_dwordx4 v[48:51], v33, s[60:61] offset:0
	global_load_dwordx4 v[52:55], v33, s[60:61] offset:16
	global_load_dwordx4 v[60:63], v4, s[42:43] offset:3136
	global_load_dwordx4 v[64:67], v33, s[60:61] offset:128
	global_load_dwordx4 v[68:71], v33, s[60:61] offset:144
	global_load_dwordx4 v[76:79], v4, s[42:43] offset:3200
	global_load_dwordx4 v[80:83], v33, s[60:61] offset:256
	global_load_dwordx4 v[84:87], v33, s[60:61] offset:272
	global_load_dwordx4 v[92:95], v4, s[42:43] offset:3264
	global_load_dwordx4 v[96:99], v33, s[60:61] offset:384
	global_load_dwordx4 v[100:103], v33, s[60:61] offset:400
	s_mov_b64 exec, -1
	s_cmp_eq_u32 s32, 0
	s_cbranch_scc1 .Lprep2_noV
	s_add_u32 s0, s40, 0x1000
	s_addc_u32 s1, s41, 0
	global_load_dwordx4 v[104:107], v4, s[0:1] offset:2624
	s_add_u32 s0, s42, 0x1000
	s_addc_u32 s1, s43, 0
	s_mov_b32 exec_lo, 0x10001
	s_mov_b32 exec_hi, 0x10001
	global_load_dwordx4 v[108:111], v4, s[0:1] offset:2624
	global_load_dwordx4 v[112:115], v33, s[62:63]
	global_load_dwordx4 v[116:119], v33, s[62:63] offset:16
	s_mov_b64 exec, -1

.LBB0_333:
	s_mov_b32 s101, s13
	s_cmpk_lg_u32 s26, 0x200
	s_cbranch_scc1 .Lprepmap_id
	s_and_b32 s100, s13, 7
	s_lshl_b32 s101, s100, 5
	s_bfe_u32 s100, s13, 0x50004
	s_add_u32 s101, s101, s100
	s_lshl_b32 s101, s101, 2
	s_bfe_u32 s100, s13, 0x10003
	s_lshl_b32 s100, s100, 1
	s_add_u32 s101, s101, s100
	s_lshr_b32 s100, s13, 9
	s_add_u32 s101, s101, s100
.Lprepmap_id:
	v_mov_b32_e32 v31, v178
	s_and_b32 s0, s101, 0xffffffc
	v_ashrrev_i32_e32 v32, 6, v31
	v_add_u32_e32 v0, s0, v32
	v_readlane_b32 s0, v236, 44
	v_and_b32_e32 v30, 15, v31
	v_readlane_b32 s1, v236, 45
	s_and_b32 s34, s101, 3
	v_bfe_u32 v33, v31, 4, 2
	v_lshl_or_b32 v8, v0, 4, v30
	v_mov_b64_e32 v[0:1], s[0:1]
	v_mad_i64_i32 v[24:25], s[0:1], v8, s78, v[0:1]
	s_cmp_lg_u32 s34, 0
	v_lshlrev_b32_e32 v0, 3, v33
	v_lshlrev_b32_e32 v2, 4, v33
	s_cbranch_scc1 .LBB0_335
	v_mov_b32_e32 v1, v3
	v_lshl_add_u64 v[6:7], v[24:25], 0, v[0:1]
	v_add_co_u32_e32 v6, vcc, 0x1000, v6
	v_add_u32_e32 v4, s15, v8
	s_nop 0
	v_addc_co_u32_e32 v7, vcc, 0, v7, vcc
	global_load_dwordx2 v[10:11], v[6:7], off offset:1536
	s_nop 0
	global_load_dwordx2 v[6:7], v[6:7], off offset:1568
	v_ashrrev_i32_e32 v5, 31, v4
	v_readlane_b32 s0, v236, 40
	v_readlane_b32 s1, v236, 41
	s_waitcnt vmcnt(1)
	v_lshlrev_b32_e32 v14, 16, v10
	v_and_b32_e32 v15, 0xffff0000, v10
	v_lshlrev_b32_e32 v16, 16, v11
	v_and_b32_e32 v17, 0xffff0000, v11
	v_lshlrev_b64 v[10:11], 6, v[4:5]
	v_lshl_add_u64 v[4:5], s[0:1], 0, v[10:11]
	v_lshl_add_u64 v[10:11], s[2:3], 0, v[10:11]
	v_lshl_add_u64 v[4:5], v[4:5], 0, v[2:3]
	v_lshl_add_u64 v[10:11], v[10:11], 0, v[2:3]
	s_waitcnt vmcnt(0)
	v_lshlrev_b32_e32 v18, 16, v6
	v_and_b32_e32 v19, 0xffff0000, v6
	v_lshlrev_b32_e32 v20, 16, v7
	v_and_b32_e32 v21, 0xffff0000, v7
	global_load_dwordx4 v[4:7], v[4:5], off
	v_readlane_b32 s0, v236, 60
	global_load_dwordx4 v[10:13], v[10:11], off
	v_readlane_b32 s1, v236, 61
	s_waitcnt vmcnt(0)
	v_pk_mul_f32 v[22:23], v[12:13], v[20:21]
	v_pk_mul_f32 v[26:27], v[10:11], v[18:19]
	v_pk_fma_f32 v[22:23], v[6:7], v[16:17], v[22:23] neg_lo:[0,0,1] neg_hi:[0,0,1]
	v_pk_fma_f32 v[26:27], v[4:5], v[14:15], v[26:27] neg_lo:[0,0,1] neg_hi:[0,0,1]
	v_pk_mul_f32 v[6:7], v[6:7], v[20:21]
	v_pk_mul_f32 v[4:5], v[4:5], v[18:19]
	v_pk_fma_f32 v[6:7], v[12:13], v[16:17], v[6:7]
	v_pk_fma_f32 v[4:5], v[10:11], v[14:15], v[4:5]
	v_cvt_pk_bf16_f32 v10, v26, v27
	v_cvt_pk_bf16_f32 v11, v22, v23
	s_nop 0
	v_cvt_pk_bf16_f32 v4, v4, v5
	v_cvt_pk_bf16_f32 v5, v6, v7
	v_mov_b64_e32 v[6:7], s[0:1]
	v_mad_i64_i32 v[6:7], s[0:1], v8, s79, v[6:7]
	v_lshl_add_u64 v[6:7], v[6:7], 0, v[0:1]
	global_store_dwordx2 v[6:7], v[10:11], off offset:128
	global_store_dwordx2 v[6:7], v[4:5], off offset:160
	global_store_dwordx2 v[6:7], v[10:11], off offset:320
	global_store_dwordx2 v[6:7], v[4:5], off offset:352
	global_store_dwordx2 v[6:7], v[10:11], off offset:512
	global_store_dwordx2 v[6:7], v[4:5], off offset:544
	global_store_dwordx2 v[6:7], v[10:11], off offset:704
	global_store_dwordx2 v[6:7], v[4:5], off offset:736
	global_store_dwordx2 v[6:7], v[10:11], off offset:896
	global_store_dwordx2 v[6:7], v[4:5], off offset:928
	global_store_dwordx2 v[6:7], v[10:11], off offset:1088
	global_store_dwordx2 v[6:7], v[4:5], off offset:1120
	global_store_dwordx2 v[6:7], v[10:11], off offset:1280
	global_store_dwordx2 v[6:7], v[4:5], off offset:1312
	global_store_dwordx2 v[6:7], v[10:11], off offset:1472
	global_store_dwordx2 v[6:7], v[4:5], off offset:1504
